# GQA loop: V tiles stored with per-16-key permutation and 144B rows so each V fragment is one ds_read_b128 (was ds_read2_b64)
# speedup vs baseline: 1.0054x; 1.0054x over previous
.LBB0_753:
	s_and_b64 vcc, exec, s[0:1]
	s_cbranch_vccz .LBB0_757
	s_waitcnt vmcnt(18)
	v_mov_b32_e32 v22, v179
	v_mov_b64_e32 v[8:9], s[66:67]
	v_and_b32_e32 v105, 31, v22
	v_ashrrev_i32_e32 v0, 1, v22
	v_and_b32_e32 v0, 0xffffffe0, v0
	v_or_b32_e32 v1, s4, v105
	v_add_u32_e32 v0, v1, v0
	v_bfe_u32 v23, v22, 5, 1
	v_mad_i64_i32 v[0:1], s[0:1], v0, s43, v[8:9]
	s_lshl_b32 s96, s3, 1
	v_lshl_add_u64 v[0:1], v[0:1], 0, s[96:97]
	v_lshlrev_b32_e32 v176, 4, v23
	v_lshl_add_u64 v[0:1], v[0:1], 0, v[176:177]
	v_ashrrev_i32_e32 v107, 3, v22
	s_mov_b32 s7, s95
	global_load_dwordx4 v[76:79], v[0:1], off offset:1536
	global_load_dwordx4 v[72:75], v[0:1], off offset:1568
	global_load_dwordx4 v[68:71], v[0:1], off offset:1600
	global_load_dwordx4 v[64:67], v[0:1], off offset:1632
	v_add_u32_e32 v0, s7, v107
	v_mad_i64_i32 v[0:1], s[0:1], v0, s43, v[8:9]
	s_lshl_b32 s96, s6, 1
	v_lshlrev_b32_e32 v2, 4, v22
	v_lshl_add_u64 v[0:1], v[0:1], 0, s[96:97]
	v_and_b32_e32 v98, 0x70, v2
	v_mov_b32_e32 v99, v177
	v_lshl_add_u64 v[0:1], v[0:1], 0, v[98:99]
	global_load_dwordx4 v[0:3], v[0:1], off
	s_movk_i32 s6, 0x2200
	v_mad_i64_i32 v[4:5], s[0:1], v107, s6, v[96:97]
	v_lshl_add_u64 v[4:5], v[4:5], 0, v[98:99]
	s_waitcnt vmcnt(20)
	v_add_u32_e32 v24, 0x100, v22
	global_load_dwordx4 v[4:7], v[4:5], off
	v_ashrrev_i32_e32 v108, 3, v24
	v_add_u32_e32 v10, s7, v108
	v_mad_i64_i32 v[8:9], s[0:1], v10, s43, v[8:9]
	v_lshl_add_u64 v[8:9], v[8:9], 0, s[96:97]
	v_lshl_add_u64 v[8:9], v[8:9], 0, v[98:99]
	global_load_dwordx4 v[8:11], v[8:9], off
	v_mad_i64_i32 v[12:13], s[0:1], v108, s6, v[96:97]
	v_lshl_add_u64 v[12:13], v[12:13], 0, v[98:99]
	global_load_dwordx4 v[12:15], v[12:13], off
	v_mad_u64_u32 v[20:21], s[0:1], v107, s42, v[98:99]
	v_mad_i64_i32 v[16:17], s[0:1], v107, s6, 0
	v_mad_i64_i32 v[18:19], s[0:1], v108, s6, 0
	v_or_b32_e32 v16, v16, v98
	v_or_b32_e32 v18, v18, v98
	v_lshlrev_b32_e32 v106, 3, v23
	v_lshlrev_b32_e32 v104, 2, v23
	v_add_u32_e32 v109, 64, v108
	v_add_u32_e32 v110, 64, v107
	s_movk_i32 s8, 0xff00
	s_movk_i32 s9, 0x4800
	s_mov_b64 s[10:11], 0x80
	v_readlane_b32 s12, v255, 5
	s_waitcnt vmcnt(3)
	ds_write_b128 v20, v[0:3]
	v_and_b32_e32 v0, -8, v22
	v_sub_u32_e32 v0, v20, v0
	v_add_u32_e32 v0, 0x4800, v0
	s_waitcnt vmcnt(2)
	ds_write2_b64 v0, v[4:5], v[6:7] offset1:1
	v_mad_u64_u32 v[0:1], s[0:1], v108, s42, v[98:99]
	s_add_u32 s0, s66, s96
	s_addc_u32 s1, s67, 0
	v_lshl_add_u64 v[96:97], s[0:1], 0, v[98:99]
	v_readlane_b32 s0, v255, 6
	v_and_b32_e32 v1, -8, v24
	s_add_i32 s0, s0, s5
	v_readlane_b32 s1, v254, 12
	s_waitcnt vmcnt(1)
	ds_write_b128 v0, v[8:11]
	v_sub_u32_e32 v0, v0, v1
	s_add_u32 s0, s1, s0
	v_readlane_b32 s1, v254, 13
	v_add_u32_e32 v0, 0x4800, v0
	s_addc_u32 s1, s1, 0
	v_mov_b32_e32 v99, 0
	s_waitcnt vmcnt(0)
	ds_write2_b64 v0, v[12:13], v[14:15] offset1:1
	v_lshl_add_u64 v[100:101], s[0:1], 0, v[16:17]
	v_lshl_add_u64 v[102:103], s[0:1], 0, v[18:19]
	s_mov_b32 s0, 0
	s_mov_b32 s5, 0
	v_mov_b32_e32 v0, 0
	v_mov_b32_e32 v1, v99
	v_mov_b32_e32 v2, v99
	v_mov_b32_e32 v3, v99
	v_mov_b32_e32 v4, v99
	v_mov_b32_e32 v5, v99
	v_mov_b32_e32 v6, v99
	v_mov_b32_e32 v7, v99
	v_mov_b32_e32 v8, v99
	v_mov_b32_e32 v9, v99
	v_mov_b32_e32 v10, v99
	v_mov_b32_e32 v11, v99
	v_mov_b32_e32 v12, v99
	v_mov_b32_e32 v13, v99
	v_mov_b32_e32 v14, v99
	v_mov_b32_e32 v15, v99
	v_mov_b32_e32 v16, 0
	v_mov_b32_e32 v17, v99
	v_mov_b32_e32 v18, v99
	v_mov_b32_e32 v19, v99
	v_mov_b32_e32 v20, v99
	v_mov_b32_e32 v21, v99
	v_mov_b32_e32 v22, v99
	v_mov_b32_e32 v23, v99
	v_mov_b32_e32 v24, v99
	v_mov_b32_e32 v25, v99
	v_mov_b32_e32 v26, v99
	v_mov_b32_e32 v27, v99
	v_mov_b32_e32 v28, v99
	v_mov_b32_e32 v29, v99
	v_mov_b32_e32 v30, v99
	v_mov_b32_e32 v31, v99
	s_waitcnt lgkmcnt(0)
	s_barrier
	v_mad_u32_u24 v156, v105, s42, v176
	v_mad_u32_u24 v157, v105, s42, v176
	v_mad_u32_u24 v188, v107, s42, v98
	v_mad_u32_u24 v189, v108, s42, v98
	v_lshrrev_b32_e32 v111, 1, v98
	v_and_b32_e32 v111, 8, v111
	v_sub_u32_e32 v111, v98, v111
	v_mad_u32_u24 v181, v107, s42, v111
	v_mad_u32_u24 v183, v108, s42, v111
	v_add_u32_e32 v157, 0x9000, v157
	v_add_u32_e32 v181, 0x9000, v181
	v_add_u32_e32 v183, 0x9000, v183
	v_mad_u32_u24 v250, v107, s34, v98
	v_mad_u32_u24 v251, v108, s34, v98
	v_add_u32_e32 v250, 0x4800, v250
	v_add_u32_e32 v251, 0x4800, v251
	ds_read2_b64 v[84:87], v250 offset1:1
	ds_read2_b64 v[80:83], v251 offset1:1
	s_waitcnt lgkmcnt(1)
	ds_write2_b64 v181, v[84:85], v[86:87] offset1:2
	s_waitcnt lgkmcnt(1)
	ds_write2_b64 v183, v[80:81], v[82:83] offset1:2
	s_waitcnt lgkmcnt(0)
	s_barrier
	v_mov_b32_e32 v144, 0
	v_mov_b32_e32 v145, 0
	v_mov_b32_e32 v146, 0
	v_mov_b32_e32 v147, 0
	v_mov_b32_e32 v148, 0
	v_mov_b32_e32 v149, 0
	v_mov_b32_e32 v150, 0
	v_mov_b32_e32 v151, 0
	v_mov_b32_e32 v152, 0
	v_mov_b32_e32 v153, 0
	v_mov_b32_e32 v154, 0
	v_mov_b32_e32 v155, 0
	v_mov_b32_e32 v160, 0
	v_mov_b32_e32 v161, 0
	v_mov_b32_e32 v162, 0
	v_mov_b32_e32 v163, 0
	v_mov_b32_e32 v164, 0
	v_mov_b32_e32 v165, 0
	v_mov_b32_e32 v166, 0
	v_mov_b32_e32 v167, 0
	v_mov_b32_e32 v168, 0
	v_mov_b32_e32 v169, 0
	v_mov_b32_e32 v170, 0
	v_mov_b32_e32 v171, 0
	v_mov_b32_e32 v184, 0
	v_mov_b32_e32 v185, 0
	v_mov_b32_e32 v186, 0
	v_mov_b32_e32 v187, 0
	v_mov_b32_e32 v196, 0
	v_mov_b32_e32 v197, 0
	v_mov_b32_e32 v198, 0
	v_mov_b32_e32 v199, 0
	v_mov_b32_e32 v200, 0
	v_mov_b32_e32 v201, 0
	v_mov_b32_e32 v202, 0
	v_mov_b32_e32 v203, 0
	v_mov_b32_e32 v204, 0
	v_mov_b32_e32 v205, 0
	v_mov_b32_e32 v206, 0
	v_mov_b32_e32 v207, 0
	v_mov_b32_e32 v246, 0
	v_mov_b32_e32 v247, 0
	v_mov_b32_e32 v248, 0
	v_mov_b32_e32 v249, 0
	v_mov_b32_e32 v32, 0xc47a0000
	v_mov_b32_e32 v33, 0xc47a0000
	v_mov_b32_e32 v34, 0xc47a0000
	v_mov_b32_e32 v35, 0xc47a0000
	v_mov_b32_e32 v36, 0xc47a0000
	v_mov_b32_e32 v37, 0xc47a0000
	v_mov_b32_e32 v38, 0xc47a0000
	v_mov_b32_e32 v39, 0xc47a0000
	v_mov_b32_e32 v40, 0xc47a0000
	v_mov_b32_e32 v41, 0xc47a0000
	v_mov_b32_e32 v42, 0xc47a0000
	v_mov_b32_e32 v43, 0xc47a0000
	v_mov_b32_e32 v44, 0xc47a0000
	v_mov_b32_e32 v45, 0xc47a0000
	v_mov_b32_e32 v46, 0xc47a0000
	v_mov_b32_e32 v47, 0xc47a0000
.Lgq_top:
	s_and_b32 s1, s0, 64
	s_mul_i32 s6, s1, 0x90
	v_add_u32_e32 v159, s6, v156
	v_add_u32_e32 v172, s6, v157
	ds_read_b128 v[112:115], v159
	ds_read_b128 v[116:119], v159 offset:32
	ds_read_b128 v[120:123], v159 offset:64
	ds_read_b128 v[124:127], v159 offset:96
	ds_read_b128 v[128:131], v159 offset:4608
	ds_read_b128 v[132:135], v159 offset:4640
	ds_read_b128 v[136:139], v159 offset:4672
	ds_read_b128 v[140:143], v159 offset:4704
	s_cmpk_eq_i32 s0, 0x10c0
	s_cbranch_scc1 .Lgq_noload
	s_cmp_lt_u32 s5, 3
	s_cselect_b32 s1, 8, 12
	s_cselect_b32 s6, 0x8000, s8
	s_lshl_b32 s1, s12, s1
	s_add_i32 s1, s6, s1
	s_add_i32 s1, s1, s0
	v_add_u32_e32 v111, s1, v110
	v_mad_i64_i32 v[250:251], s[6:7], v111, s43, v[96:97]
	v_add_u32_e32 v111, s1, v109
	global_load_dwordx4 v[92:95], v[250:251], off
	global_load_dwordx4 v[84:87], v[100:101], off
	v_mad_i64_i32 v[250:251], s[6:7], v111, s43, v[96:97]
	s_nop 0
	global_load_dwordx4 v[88:91], v[250:251], off
	global_load_dwordx4 v[80:83], v[102:103], off
	v_lshl_add_u64 v[100:101], v[100:101], 0, s[10:11]
	v_lshl_add_u64 v[102:103], v[102:103], 0, s[10:11]
.Lgq_noload:
	v_exp_f32_e32 v32, v32
	v_exp_f32_e32 v33, v33
	v_exp_f32_e32 v34, v34
	v_exp_f32_e32 v35, v35
	s_waitcnt lgkmcnt(7)
	v_mfma_f32_32x32x16_bf16 v[48:63], v[112:115], v[76:79], 0
	v_exp_f32_e32 v36, v36
	v_exp_f32_e32 v37, v37
	v_add_f32_e32 v246, v32, v246
	v_add_f32_e32 v247, v33, v247
	v_cvt_pk_bf16_f32 v238, v32, v33
	s_waitcnt lgkmcnt(6)
	v_mfma_f32_32x32x16_bf16 v[48:63], v[116:119], v[72:75], v[48:63]
	v_exp_f32_e32 v38, v38
	v_exp_f32_e32 v39, v39
	v_add_f32_e32 v248, v34, v248
	v_add_f32_e32 v249, v35, v249
	v_cvt_pk_bf16_f32 v239, v34, v35
	s_waitcnt lgkmcnt(5)
	v_mfma_f32_32x32x16_bf16 v[48:63], v[120:123], v[68:71], v[48:63]
	v_exp_f32_e32 v40, v40
	v_exp_f32_e32 v41, v41
	v_add_f32_e32 v246, v36, v246
	v_add_f32_e32 v247, v37, v247
	v_cvt_pk_bf16_f32 v240, v36, v37
	s_waitcnt lgkmcnt(4)
	v_mfma_f32_32x32x16_bf16 v[48:63], v[124:127], v[64:67], v[48:63]
	v_exp_f32_e32 v42, v42
	v_exp_f32_e32 v43, v43
	v_add_f32_e32 v248, v38, v248
	v_add_f32_e32 v249, v39, v249
	v_cvt_pk_bf16_f32 v241, v38, v39
	v_mfma_f32_32x32x16_bf16 v[0:15], v[144:147], v[200:203], v[0:15]
	ds_read_b128 v[144:147], v172
	v_exp_f32_e32 v44, v44
	v_exp_f32_e32 v45, v45
	v_add_f32_e32 v246, v40, v246
	v_add_f32_e32 v247, v41, v247
	v_cvt_pk_bf16_f32 v242, v40, v41
	v_mfma_f32_32x32x16_bf16 v[16:31], v[164:167], v[200:203], v[16:31]
	ds_read_b128 v[164:167], v172 offset:4608
	v_exp_f32_e32 v46, v46
	v_exp_f32_e32 v47, v47
	v_add_f32_e32 v248, v42, v248
	v_add_f32_e32 v249, v43, v249
	v_cvt_pk_bf16_f32 v243, v42, v43
	v_mfma_f32_32x32x16_bf16 v[0:15], v[148:151], v[204:207], v[0:15]
	ds_read_b128 v[148:151], v172 offset:32
	v_add_f32_e32 v246, v44, v246
	v_add_f32_e32 v247, v45, v247
	v_cvt_pk_bf16_f32 v244, v44, v45
	v_add_f32_e32 v248, v46, v248
	v_add_f32_e32 v249, v47, v249
	v_mfma_f32_32x32x16_bf16 v[16:31], v[168:171], v[204:207], v[16:31]
	ds_read_b128 v[168:171], v172 offset:4640
	v_cvt_pk_bf16_f32 v245, v46, v47
	v_exp_f32_e32 v48, v48
	v_exp_f32_e32 v49, v49
	v_exp_f32_e32 v50, v50
	s_waitcnt lgkmcnt(7)
	v_mfma_f32_32x32x16_bf16 v[32:47], v[128:131], v[76:79], 0
	v_exp_f32_e32 v51, v51
	v_exp_f32_e32 v52, v52
	v_add_f32_e32 v246, v48, v246
	v_add_f32_e32 v247, v49, v247
	v_cvt_pk_bf16_f32 v200, v48, v49
	s_waitcnt lgkmcnt(6)
	v_mfma_f32_32x32x16_bf16 v[32:47], v[132:135], v[72:75], v[32:47]
	v_exp_f32_e32 v53, v53
	v_exp_f32_e32 v54, v54
	v_add_f32_e32 v248, v50, v248
	v_add_f32_e32 v249, v51, v249
	v_cvt_pk_bf16_f32 v201, v50, v51
	s_waitcnt lgkmcnt(5)
	v_mfma_f32_32x32x16_bf16 v[32:47], v[136:139], v[68:71], v[32:47]
	v_exp_f32_e32 v55, v55
	v_exp_f32_e32 v56, v56
	v_add_f32_e32 v246, v52, v246
	v_add_f32_e32 v247, v53, v247
	v_cvt_pk_bf16_f32 v202, v52, v53
	s_waitcnt lgkmcnt(4)
	v_mfma_f32_32x32x16_bf16 v[32:47], v[140:143], v[64:67], v[32:47]
	v_exp_f32_e32 v57, v57
	v_exp_f32_e32 v58, v58
	v_add_f32_e32 v248, v54, v248
	v_add_f32_e32 v249, v55, v249
	v_cvt_pk_bf16_f32 v203, v54, v55
	v_mfma_f32_32x32x16_bf16 v[0:15], v[152:155], v[238:241], v[0:15]
	ds_read_b128 v[152:155], v172 offset:64
	v_exp_f32_e32 v59, v59
	v_exp_f32_e32 v60, v60
	v_add_f32_e32 v246, v56, v246
	v_add_f32_e32 v247, v57, v247
	v_cvt_pk_bf16_f32 v204, v56, v57
	v_mfma_f32_32x32x16_bf16 v[16:31], v[184:187], v[238:241], v[16:31]
	ds_read_b128 v[184:187], v172 offset:4672
	v_exp_f32_e32 v61, v61
	v_exp_f32_e32 v62, v62
	v_add_f32_e32 v248, v58, v248
	v_add_f32_e32 v249, v59, v249
	v_cvt_pk_bf16_f32 v205, v58, v59
	v_mfma_f32_32x32x16_bf16 v[0:15], v[160:163], v[242:245], v[0:15]
	ds_read_b128 v[160:163], v172 offset:96
	v_exp_f32_e32 v63, v63
	v_add_f32_e32 v246, v60, v246
	v_add_f32_e32 v247, v61, v247
	v_cvt_pk_bf16_f32 v206, v60, v61
	v_add_f32_e32 v248, v62, v248
	v_mfma_f32_32x32x16_bf16 v[16:31], v[196:199], v[242:245], v[16:31]
	ds_read_b128 v[196:199], v172 offset:4704
	v_add_f32_e32 v249, v63, v249
	v_cvt_pk_bf16_f32 v207, v62, v63
	s_cmpk_eq_i32 s0, 0x10c0
	s_cbranch_scc1 .Lgq_nostore
	s_and_b32 s1, s0, 64
	s_xor_b32 s1, s1, 64
	s_mul_i32 s6, s1, 0x90
	v_add_u32_e32 v111, s6, v188
	v_add_u32_e32 v250, s6, v181
	v_add_u32_e32 v251, s6, v189
	v_add_u32_e32 v237, s6, v183
	s_waitcnt vmcnt(3)
	ds_write_b128 v111, v[92:95]
	s_waitcnt vmcnt(2)
	ds_write2_b64 v250, v[84:85], v[86:87] offset1:2
	s_waitcnt vmcnt(1)
	ds_write_b128 v251, v[88:91]
	s_waitcnt vmcnt(0)
	ds_write2_b64 v237, v[80:81], v[82:83] offset1:2
